# grid barrier: pollers issue the acquire L1 invalidate before spinning (overlaps the wait)
# speedup vs baseline: 1.0246x; 1.0092x over previous
.LBB0_41:
	s_or_b64 exec, exec, s[2:3]
	v_cvt_f32_u32_e32 v4, v2
	s_waitcnt vmcnt(0)
	v_readfirstlane_b32 s2, v3
	v_rcp_iflag_f32_e32 v4, v4
	s_nop 0
	v_add_u32_e32 v1, s2, v1
	v_add_u32_e32 v5, 1, v1
	v_mul_f32_e32 v3, 0x4f7ffffe, v4
	v_cvt_u32_f32_e32 v3, v3
	v_sub_u32_e32 v4, 0, v2
	v_mul_lo_u32 v4, v4, v3
	v_mul_hi_u32 v4, v3, v4
	v_add_u32_e32 v3, v3, v4
	v_mul_hi_u32 v3, v1, v3
	v_mul_lo_u32 v4, v3, v2
	v_sub_u32_e32 v1, v1, v4
	v_add_u32_e32 v6, 1, v3
	v_cmp_ge_u32_e32 vcc, v1, v2
	v_sub_u32_e32 v4, v1, v2
	s_nop 0
	v_cndmask_b32_e32 v3, v3, v6, vcc
	v_cndmask_b32_e32 v1, v1, v4, vcc
	v_add_u32_e32 v4, 1, v3
	v_cmp_ge_u32_e32 vcc, v1, v2
	s_nop 1
	v_cndmask_b32_e32 v1, v3, v4, vcc
	v_mad_u64_u32 v[2:3], s[2:3], v2, v1, v[2:3]
	v_cmp_ne_u32_e32 vcc, v5, v2
	s_and_saveexec_b64 s[2:3], vcc
	s_xor_b64 s[2:3], exec, s[2:3]
	s_cbranch_execz .LBB0_55
	v_readlane_b32 s4, v251, 41
	v_readlane_b32 s5, v251, 42
	s_waitcnt lgkmcnt(0)
	s_nop 3
	buffer_inv sc1
	global_load_dword v0, v193, s[4:5] sc1
	s_waitcnt vmcnt(0)
	v_cmp_eq_u32_e32 vcc, v0, v1
	s_and_saveexec_b64 s[4:5], vcc
	s_cbranch_execz .LBB0_54
	s_mov_b32 s31, 1
	s_mov_b64 s[10:11], 0
	s_branch .LBB0_45

.LBB0_54:
	s_or_b64 exec, exec, s[4:5]
	s_waitcnt vmcnt(0)
	s_waitcnt vmcnt(0)
